# plus: da_lambda as straight-line code (all operand loads in flight, same fma order), scalar prefetch of the next page-table entry in the decode page loop
# speedup vs baseline: 1.0115x; 1.0009x over previous
.LBB0_671:
	s_cmp_lt_i32 s44, 3
	s_cselect_b64 s[0:1], -1, 0
	s_cmp_gt_i32 s45, 2
	s_cselect_b64 s[2:3], -1, 0
	s_and_b64 s[0:1], s[0:1], s[2:3]
	s_andn2_b64 vcc, exec, s[0:1]
	s_cbranch_vccnz .LBB0_887
	v_writelane_b32 v254, s68, 57
	v_mov_b32_e32 v1, 0
	s_mov_b64 s[0:1], 0
	v_writelane_b32 v254, s69, 58
	v_mov_b32_e32 v138, 0
	v_readlane_b32 s4, v254, 11
	v_readlane_b32 s12, v254, 19
	v_readlane_b32 s13, v254, 20
	v_readlane_b32 s14, v254, 21
	v_readlane_b32 s15, v254, 22
	v_readlane_b32 s16, v254, 23
	v_readlane_b32 s17, v254, 24
	v_readlane_b32 s18, v254, 25
	v_readlane_b32 s19, v254, 26
	s_mov_b64 s[12:13], s[16:17]
	s_mov_b64 s[14:15], s[18:19]
	v_readlane_b32 s16, v254, 28
	v_readlane_b32 s5, v254, 12
	v_readlane_b32 s6, v254, 13
	v_readlane_b32 s7, v254, 14
	v_readlane_b32 s8, v254, 15
	v_readlane_b32 s9, v254, 16
	v_readlane_b32 s10, v254, 17
	v_readlane_b32 s11, v254, 18
	v_readlane_b32 s17, v254, 29
	v_readlane_b32 s18, v254, 30
	v_readlane_b32 s19, v254, 31
	v_readlane_b32 s20, v254, 32
	v_readlane_b32 s21, v254, 33
	v_readlane_b32 s22, v254, 34
	v_readlane_b32 s23, v254, 35
	v_readlane_b32 s24, v254, 36
	v_readlane_b32 s25, v254, 37
	s_mov_b64 s[4:5], s[16:17]
	v_mov_b32_e32 v139, v1
	s_mov_b64 s[6:7], s[18:19]
	s_mov_b64 s[8:9], s[20:21]
	v_readlane_b32 s26, v254, 38
	v_readlane_b32 s27, v254, 39
	v_readlane_b32 s28, v254, 40
	v_readlane_b32 s29, v254, 41
	v_readlane_b32 s30, v254, 42
	v_readlane_b32 s31, v254, 43
	s_mov_b64 s[10:11], s[22:23]
	s_mov_b64 s[12:13], s[24:25]
	global_load_dwordx4 v[2:5], v1, s[14:15]
	global_load_dwordx4 v[34:37], v1, s[4:5]
	global_load_dwordx4 v[66:69], v1, s[6:7]
	global_load_dwordx4 v[98:101], v1, s[8:9]
	global_load_dwordx4 v[6:9], v1, s[14:15] offset:16
	global_load_dwordx4 v[38:41], v1, s[4:5] offset:16
	global_load_dwordx4 v[70:73], v1, s[6:7] offset:16
	global_load_dwordx4 v[102:105], v1, s[8:9] offset:16
	global_load_dwordx4 v[10:13], v1, s[14:15] offset:32
	global_load_dwordx4 v[42:45], v1, s[4:5] offset:32
	global_load_dwordx4 v[74:77], v1, s[6:7] offset:32
	global_load_dwordx4 v[106:109], v1, s[8:9] offset:32
	global_load_dwordx4 v[14:17], v1, s[14:15] offset:48
	global_load_dwordx4 v[46:49], v1, s[4:5] offset:48
	global_load_dwordx4 v[78:81], v1, s[6:7] offset:48
	global_load_dwordx4 v[110:113], v1, s[8:9] offset:48
	global_load_dwordx4 v[18:21], v1, s[14:15] offset:64
	global_load_dwordx4 v[50:53], v1, s[4:5] offset:64
	global_load_dwordx4 v[82:85], v1, s[6:7] offset:64
	global_load_dwordx4 v[114:117], v1, s[8:9] offset:64
	global_load_dwordx4 v[22:25], v1, s[14:15] offset:80
	global_load_dwordx4 v[54:57], v1, s[4:5] offset:80
	global_load_dwordx4 v[86:89], v1, s[6:7] offset:80
	global_load_dwordx4 v[118:121], v1, s[8:9] offset:80
	global_load_dwordx4 v[26:29], v1, s[14:15] offset:96
	global_load_dwordx4 v[58:61], v1, s[4:5] offset:96
	global_load_dwordx4 v[90:93], v1, s[6:7] offset:96
	global_load_dwordx4 v[122:125], v1, s[8:9] offset:96
	global_load_dwordx4 v[30:33], v1, s[14:15] offset:112
	global_load_dwordx4 v[62:65], v1, s[4:5] offset:112
	global_load_dwordx4 v[94:97], v1, s[6:7] offset:112
	global_load_dwordx4 v[126:129], v1, s[8:9] offset:112
	global_load_dwordx4 v[140:143], v1, s[14:15] offset:128
	global_load_dwordx4 v[164:167], v1, s[4:5] offset:128
	global_load_dwordx4 v[188:191], v1, s[6:7] offset:128
	global_load_dwordx4 v[212:215], v1, s[8:9] offset:128
	global_load_dwordx4 v[144:147], v1, s[14:15] offset:144
	global_load_dwordx4 v[168:171], v1, s[4:5] offset:144
	global_load_dwordx4 v[192:195], v1, s[6:7] offset:144
	global_load_dwordx4 v[216:219], v1, s[8:9] offset:144
	global_load_dwordx4 v[148:151], v1, s[14:15] offset:160
	global_load_dwordx4 v[172:175], v1, s[4:5] offset:160
	global_load_dwordx4 v[196:199], v1, s[6:7] offset:160
	global_load_dwordx4 v[220:223], v1, s[8:9] offset:160
	global_load_dwordx4 v[152:155], v1, s[14:15] offset:176
	global_load_dwordx4 v[176:179], v1, s[4:5] offset:176
	global_load_dwordx4 v[200:203], v1, s[6:7] offset:176
	global_load_dwordx4 v[224:227], v1, s[8:9] offset:176
	global_load_dwordx4 v[156:159], v1, s[14:15] offset:192
	global_load_dwordx4 v[180:183], v1, s[4:5] offset:192
	global_load_dwordx4 v[204:207], v1, s[6:7] offset:192
	global_load_dwordx4 v[228:231], v1, s[8:9] offset:192
	global_load_dwordx4 v[160:163], v1, s[14:15] offset:208
	global_load_dwordx4 v[184:187], v1, s[4:5] offset:208
	global_load_dwordx4 v[208:211], v1, s[6:7] offset:208
	global_load_dwordx4 v[232:235], v1, s[8:9] offset:208
	s_waitcnt vmcnt(24)
	v_fma_f32 v139, v2, v34, v139
	v_fma_f32 v138, v66, v98, v138
	v_fma_f32 v139, v3, v35, v139
	v_fma_f32 v138, v67, v99, v138
	v_fma_f32 v139, v4, v36, v139
	v_fma_f32 v138, v68, v100, v138
	v_fma_f32 v139, v5, v37, v139
	v_fma_f32 v138, v69, v101, v138
	v_fma_f32 v139, v6, v38, v139
	v_fma_f32 v138, v70, v102, v138
	v_fma_f32 v139, v7, v39, v139
	v_fma_f32 v138, v71, v103, v138
	v_fma_f32 v139, v8, v40, v139
	v_fma_f32 v138, v72, v104, v138
	v_fma_f32 v139, v9, v41, v139
	v_fma_f32 v138, v73, v105, v138
	v_fma_f32 v139, v10, v42, v139
	v_fma_f32 v138, v74, v106, v138
	v_fma_f32 v139, v11, v43, v139
	v_fma_f32 v138, v75, v107, v138
	v_fma_f32 v139, v12, v44, v139
	v_fma_f32 v138, v76, v108, v138
	v_fma_f32 v139, v13, v45, v139
	v_fma_f32 v138, v77, v109, v138
	v_fma_f32 v139, v14, v46, v139
	v_fma_f32 v138, v78, v110, v138
	v_fma_f32 v139, v15, v47, v139
	v_fma_f32 v138, v79, v111, v138
	v_fma_f32 v139, v16, v48, v139
	v_fma_f32 v138, v80, v112, v138
	v_fma_f32 v139, v17, v49, v139
	v_fma_f32 v138, v81, v113, v138
	v_fma_f32 v139, v18, v50, v139
	v_fma_f32 v138, v82, v114, v138
	v_fma_f32 v139, v19, v51, v139
	v_fma_f32 v138, v83, v115, v138
	v_fma_f32 v139, v20, v52, v139
	v_fma_f32 v138, v84, v116, v138
	v_fma_f32 v139, v21, v53, v139
	v_fma_f32 v138, v85, v117, v138
	v_fma_f32 v139, v22, v54, v139
	v_fma_f32 v138, v86, v118, v138
	v_fma_f32 v139, v23, v55, v139
	v_fma_f32 v138, v87, v119, v138
	v_fma_f32 v139, v24, v56, v139
	v_fma_f32 v138, v88, v120, v138
	v_fma_f32 v139, v25, v57, v139
	v_fma_f32 v138, v89, v121, v138
	v_fma_f32 v139, v26, v58, v139
	v_fma_f32 v138, v90, v122, v138
	v_fma_f32 v139, v27, v59, v139
	v_fma_f32 v138, v91, v123, v138
	v_fma_f32 v139, v28, v60, v139
	v_fma_f32 v138, v92, v124, v138
	v_fma_f32 v139, v29, v61, v139
	v_fma_f32 v138, v93, v125, v138
	v_fma_f32 v139, v30, v62, v139
	v_fma_f32 v138, v94, v126, v138
	v_fma_f32 v139, v31, v63, v139
	v_fma_f32 v138, v95, v127, v138
	v_fma_f32 v139, v32, v64, v139
	v_fma_f32 v138, v96, v128, v138
	v_fma_f32 v139, v33, v65, v139
	v_fma_f32 v138, v97, v129, v138
	global_load_dwordx4 v[2:5], v1, s[14:15] offset:224
	global_load_dwordx4 v[34:37], v1, s[4:5] offset:224
	global_load_dwordx4 v[66:69], v1, s[6:7] offset:224
	global_load_dwordx4 v[98:101], v1, s[8:9] offset:224
	global_load_dwordx4 v[6:9], v1, s[14:15] offset:240
	global_load_dwordx4 v[38:41], v1, s[4:5] offset:240
	global_load_dwordx4 v[70:73], v1, s[6:7] offset:240
	global_load_dwordx4 v[102:105], v1, s[8:9] offset:240
	s_waitcnt vmcnt(8)
	v_fma_f32 v139, v140, v164, v139
	v_fma_f32 v138, v188, v212, v138
	v_fma_f32 v139, v141, v165, v139
	v_fma_f32 v138, v189, v213, v138
	v_fma_f32 v139, v142, v166, v139
	v_fma_f32 v138, v190, v214, v138
	v_fma_f32 v139, v143, v167, v139
	v_fma_f32 v138, v191, v215, v138
	v_fma_f32 v139, v144, v168, v139
	v_fma_f32 v138, v192, v216, v138
	v_fma_f32 v139, v145, v169, v139
	v_fma_f32 v138, v193, v217, v138
	v_fma_f32 v139, v146, v170, v139
	v_fma_f32 v138, v194, v218, v138
	v_fma_f32 v139, v147, v171, v139
	v_fma_f32 v138, v195, v219, v138
	v_fma_f32 v139, v148, v172, v139
	v_fma_f32 v138, v196, v220, v138
	v_fma_f32 v139, v149, v173, v139
	v_fma_f32 v138, v197, v221, v138
	v_fma_f32 v139, v150, v174, v139
	v_fma_f32 v138, v198, v222, v138
	v_fma_f32 v139, v151, v175, v139
	v_fma_f32 v138, v199, v223, v138
	v_fma_f32 v139, v152, v176, v139
	v_fma_f32 v138, v200, v224, v138
	v_fma_f32 v139, v153, v177, v139
	v_fma_f32 v138, v201, v225, v138
	v_fma_f32 v139, v154, v178, v139
	v_fma_f32 v138, v202, v226, v138
	v_fma_f32 v139, v155, v179, v139
	v_fma_f32 v138, v203, v227, v138
	v_fma_f32 v139, v156, v180, v139
	v_fma_f32 v138, v204, v228, v138
	v_fma_f32 v139, v157, v181, v139
	v_fma_f32 v138, v205, v229, v138
	v_fma_f32 v139, v158, v182, v139
	v_fma_f32 v138, v206, v230, v138
	v_fma_f32 v139, v159, v183, v139
	v_fma_f32 v138, v207, v231, v138
	v_fma_f32 v139, v160, v184, v139
	v_fma_f32 v138, v208, v232, v138
	v_fma_f32 v139, v161, v185, v139
	v_fma_f32 v138, v209, v233, v138
	v_fma_f32 v139, v162, v186, v139
	v_fma_f32 v138, v210, v234, v138
	v_fma_f32 v139, v163, v187, v139
	v_fma_f32 v138, v211, v235, v138
	s_waitcnt vmcnt(0)
	v_fma_f32 v139, v2, v34, v139
	v_fma_f32 v138, v66, v98, v138
	v_fma_f32 v139, v3, v35, v139
	v_fma_f32 v138, v67, v99, v138
	v_fma_f32 v139, v4, v36, v139
	v_fma_f32 v138, v68, v100, v138
	v_fma_f32 v139, v5, v37, v139
	v_fma_f32 v138, v69, v101, v138
	v_fma_f32 v139, v6, v38, v139
	v_fma_f32 v138, v70, v102, v138
	v_fma_f32 v139, v7, v39, v139
	v_fma_f32 v138, v71, v103, v138
	v_fma_f32 v139, v8, v40, v139
	v_fma_f32 v138, v72, v104, v138
	v_fma_f32 v139, v9, v41, v139
	v_fma_f32 v138, v73, v105, v138
	s_bitcmp0_b32 s43, 3
	v_readlane_b32 s0, v254, 2
	s_cselect_b64 s[2:3], -1, 0
	s_cmpk_lt_i32 s0, 0x80
	s_cselect_b64 s[0:1], -1, 0
	v_writelane_b32 v254, s2, 59
	s_or_b64 s[0:1], s[2:3], s[0:1]
	s_xor_b64 s[4:5], s[0:1], -1
	v_writelane_b32 v254, s3, 60
	s_bitcmp0_b32 s46, 0
	v_readlane_b32 s2, v254, 57
	s_cselect_b64 s[0:1], -1, 0
	v_readlane_b32 s3, v254, 58
	s_add_u32 s44, s2, 0xb000000
	s_addc_u32 s45, s3, 0
	s_add_u32 s24, s2, 0x18c00000
	s_addc_u32 s25, s3, 0
	s_add_u32 s26, s2, 0x16800000
	s_addc_u32 s27, s3, 0
	v_writelane_b32 v254, s4, 61
	s_or_b64 s[0:1], s[0:1], s[4:5]
	s_mov_b32 s89, 0
	v_writelane_b32 v254, s5, 62
	s_and_b64 vcc, exec, s[0:1]
	s_cbranch_vccnz .LBB0_694
	v_readlane_b32 s0, v254, 44
	v_readlane_b32 s6, v254, 50
	v_readlane_b32 s7, v254, 51
	s_add_u32 s0, s6, 0x8080000
	v_readlane_b32 s1, v254, 45
	v_readlane_b32 s2, v254, 46
	v_readlane_b32 s3, v254, 47
	v_readlane_b32 s4, v254, 48
	v_readlane_b32 s5, v254, 49
	v_writelane_b32 v254, s0, 63
	s_addc_u32 s0, s7, 0
	v_writelane_b32 v255, s0, 1
	s_add_i32 s0, 0, 0x20140
	v_mbcnt_lo_u32_b32 v2, -1, 0
	v_mov_b32_e32 v75, 0
	v_writelane_b32 v255, s0, 2
	v_mov_b32_e32 v1, s0
	s_movk_i32 s33, 0x5800
	s_movk_i32 s93, 0x1000
	s_mov_b64 s[52:53], 0x5800
	s_movk_i32 s90, 0x5000
	s_mov_b64 s[54:55], 0xb000
	s_mov_b32 s91, 0xb000
	s_mov_b64 s[56:57], 0x10800
	s_mov_b32 s48, 0x10000
	s_mov_b64 s[62:63], 0x16000
	s_mov_b32 s49, 0x16000
	s_mov_b64 s[64:65], 0x1b800
	s_mov_b32 s95, 0x1b000
	s_mov_b64 s[66:67], 0x21000
	s_mov_b32 s88, 0x21000
	s_mov_b64 s[68:69], 0x26800
	s_mov_b32 s70, 0x26000
	s_mov_b64 s[96:97], 0x1000
	s_movk_i32 s71, 0x110
	s_add_i32 s72, 0, 0x11400
	s_mov_b32 s92, 0x3fb8aa3b
	v_mov_b32_e32 v99, 0x358637bd
	v_mov_b32_e32 v110, 0x260
	v_mbcnt_hi_u32_b32 v111, -1, v2
	s_branch .LBB0_678

.LBB0_719:
	s_or_b64 exec, exec, s[2:3]
	s_waitcnt lgkmcnt(0)
	s_barrier
	ds_read_b32 v2, v1
	s_mov_b64 s[2:3], -1
	s_waitcnt lgkmcnt(0)
	s_barrier
	v_readfirstlane_b32 s6, v2
	s_cmpk_gt_i32 s6, 0x7f
	s_cbranch_scc1 .LBB0_714
	v_mov_b32_e32 v244, v0
	v_readlane_b32 s16, v254, 28
	v_readfirstlane_b32 s2, v244
	s_ashr_i32 s4, s2, 6
	v_and_b32_e32 v140, 8, v244
	s_ashr_i32 s5, s4, 31
	v_lshl_add_u64 v[2:3], v[140:141], 0, s[4:5]
	v_readlane_b32 s24, v254, 36
	v_readlane_b32 s25, v254, 37
	s_ashr_i32 s3, s6, 31
	s_lshr_b32 s3, s3, 25
	v_lshl_add_u64 v[10:11], v[2:3], 2, s[24:25]
	global_load_dword v14, v[10:11], off offset:1984
	s_add_i32 s3, s6, s3
	v_readlane_b32 s12, v254, 57
	s_and_b32 s7, s3, 0xff80
	v_readlane_b32 s13, v254, 58
	v_bfe_u32 v6, v244, 4, 2
	v_and_b32_e32 v7, 7, v244
	s_lshl_b32 s11, s2, 2
	s_sub_i32 s6, s6, s7
	v_mov_b64_e32 v[2:3], s[12:13]
	v_or_b32_e32 v9, 0x80, v7
	v_lshlrev_b32_e32 v13, 2, v6
	s_mul_i32 s7, s4, 0x2400
	s_and_b32 s11, s11, 0xffffff00
	s_bfe_i32 s13, s6, 0x80000
	v_and_b32_e32 v245, 15, v244
	v_and_b32_e32 v8, 31, v244
	v_bfe_u32 v4, v244, 2, 2
	v_sub_u32_e32 v17, v9, v13
	s_add_i32 s7, s7, 0
	v_lshl_add_u32 v9, v6, 12, s11
	s_bfe_u32 s11, s13, 0x4000b
	v_or_b32_e32 v16, v13, v4
	v_lshl_or_b32 v247, v245, 4, v9
	v_mov_b32_e32 v9, s7
	v_lshl_add_u32 v26, v8, 3, s7
	s_add_i32 s7, s6, s11
	s_movk_i32 s11, 0x120
	v_bfe_u32 v15, v244, 5, 1
	s_lshl_b32 s12, s4, 9
	v_mad_u32_u24 v31, v16, s11, v9
	s_bfe_i32 s11, s7, 0x80000
	v_readlane_b32 s21, v254, 33
	v_lshl_add_u32 v18, v15, 12, s12
	s_sext_i32_i16 s12, s11
	s_and_b32 s7, s7, 0xfff0
	s_ashr_i32 s21, s12, 4
	s_sub_i32 s11, s6, s7
	s_lshl_b32 s7, s21, 3
	v_add_u32_e32 v12, s4, v140
	s_addk_i32 s7, 0x2000
	v_lshlrev_b32_e32 v5, 3, v244
	v_lshlrev_b32_e32 v4, 6, v12
	v_mad_u32_u24 v29, v6, s34, v9
	v_or_b32_e32 v6, s7, v7
	s_movk_i32 s7, 0x5800
	v_and_b32_e32 v21, 24, v5
	v_subrev_u32_e32 v23, 18, v17
	v_ashrrev_i32_e32 v5, 31, v4
	v_mad_u64_u32 v[2:3], s[12:13], v6, s7, v[2:3]
	v_and_b32_e32 v140, 48, v244
	v_subrev_u32_e32 v24, 19, v17
	v_cmp_lt_u32_e32 vcc, s36, v23
	v_lshl_add_u64 v[2:3], v[4:5], 1, v[2:3]
	v_lshl_add_u64 v[2:3], v[2:3], 0, v[140:141]
	v_cndmask_b32_e32 v27, v237, v238, vcc
	v_cmp_lt_u32_e32 vcc, s36, v24
	s_mov_b64 s[12:13], 0xb002000
	s_mov_b32 s7, 0xb002000
	v_cndmask_b32_e32 v28, v237, v238, vcc
	v_lshl_add_u64 v[6:7], v[2:3], 0, s[12:13]
	v_add_co_u32_e32 v2, vcc, s7, v2
	v_subrev_u32_e32 v25, 32, v17
	s_nop 0
	v_addc_co_u32_e32 v3, vcc, 0, v3, vcc
	v_cmp_lt_u32_e32 vcc, s37, v25
	s_movk_i32 s7, 0xffb3
	v_lshl_or_b32 v248, v8, 4, v18
	v_mad_u32_u24 v30, v245, s34, v9
	global_load_dwordx4 v[2:5], v[2:3], off
	s_nop 0
	global_load_dwordx4 v[6:9], v[6:7], off offset:64
	v_add_u32_e32 v50, 0xffffff8f, v17
	v_add_u32_e32 v52, 0xffffff8e, v17
	v_add_u32_e32 v54, 0xffffff8d, v17
	v_add_u32_e32 v19, 0xffffff7f, v17
	v_ashrrev_i32_e32 v13, 31, v12
	v_add_u32_e32 v22, 0xffffff7e, v17
	v_lshl_add_u64 v[146:147], v[12:13], 2, s[24:25]
	v_mov_b32_e32 v13, v141
	s_waitcnt vmcnt(2)
	v_mul_f32_e32 v142, 0x3fb8aa3b, v14
	v_cndmask_b32_e64 v14, 28, 29, vcc
	v_cmp_lt_u32_e32 vcc, s36, v25
	s_sext_i32_i8 s6, s11
	v_readlane_b32 s22, v254, 34
	v_addc_co_u32_e32 v25, vcc, 0, v14, vcc
	v_subrev_u32_e32 v14, 33, v17
	v_cmp_lt_u32_e32 vcc, s37, v14
	s_lshl_b32 s6, s6, 3
	s_lshl_b32 s38, s21, 7
	v_cndmask_b32_e64 v16, 28, 29, vcc
	v_cmp_lt_u32_e32 vcc, s36, v14
	v_subrev_u32_e32 v14, 34, v17
	v_readlane_b32 s23, v254, 35
	v_addc_co_u32_e32 v32, vcc, 0, v16, vcc
	v_cmp_lt_u32_e32 vcc, s37, v14
	v_readlane_b32 s26, v254, 38
	v_readlane_b32 s27, v254, 39
	v_cndmask_b32_e64 v16, 28, 29, vcc
	v_cmp_lt_u32_e32 vcc, s36, v14
	v_subrev_u32_e32 v14, 35, v17
	v_readlane_b32 s28, v254, 40
	v_addc_co_u32_e32 v33, vcc, 0, v16, vcc
	v_cmp_lt_u32_e32 vcc, s37, v14
	v_readlane_b32 s29, v254, 41
	v_readlane_b32 s30, v254, 42
	v_cndmask_b32_e64 v16, 28, 29, vcc
	v_cmp_lt_u32_e32 vcc, s36, v14
	v_subrev_u32_e32 v14, 48, v17
	v_readlane_b32 s31, v254, 43
	v_addc_co_u32_e32 v34, vcc, 0, v16, vcc
	v_cmp_lt_u32_e32 vcc, s40, v14
	s_add_i32 s22, s38, s6
	v_readlane_b32 s20, v254, 32
	v_cndmask_b32_e64 v16, 27, 28, vcc
	v_cmp_lt_u32_e32 vcc, s37, v14
	v_add_u32_e32 v14, 0xffffff82, v17
	s_ashr_i32 s23, s22, 31
	v_addc_co_u32_e32 v35, vcc, 0, v16, vcc
	v_cmp_gt_u32_e32 vcc, s7, v14
	v_mov_b32_e32 v14, 0x6c0
	v_subrev_u32_e32 v16, 50, v17
	v_cndmask_b32_e32 v14, v14, v239, vcc
	v_cmp_lt_u32_e32 vcc, s41, v16
	v_readlane_b32 s24, v254, 44
	s_ashr_i32 s20, s3, 7
	v_cndmask_b32_e64 v18, 26, 27, vcc
	v_cmp_lt_u32_e32 vcc, s40, v16
	v_subrev_u32_e32 v16, 51, v17
	s_sub_i32 s39, 0x7f, s6
	v_addc_co_u32_e32 v36, vcc, 0, v18, vcc
	v_cmp_lt_u32_e32 vcc, s41, v16
	s_lshl_b64 s[6:7], s[22:23], 2
	v_readlane_b32 s28, v254, 48
	v_cndmask_b32_e64 v18, 26, 27, vcc
	v_cmp_lt_u32_e32 vcc, s40, v16
	v_subrev_u32_e32 v16, 64, v17
	v_readlane_b32 s30, v254, 50
	v_addc_co_u32_e32 v37, vcc, 0, v18, vcc
	v_cmp_lt_u32_e32 vcc, 58, v16
	v_lshlrev_b32_e32 v20, 3, v245
	v_mul_u32_u24_e32 v56, 0x120, v15
	v_cndmask_b32_e64 v18, 25, 26, vcc
	v_cmp_lt_u32_e32 vcc, s41, v16
	v_add_u32_e32 v16, 0xffffffbf, v17
	v_mov_b32_e32 v15, v141
	v_addc_co_u32_e32 v38, vcc, 0, v18, vcc
	v_cmp_lt_u32_e32 vcc, 51, v16
	v_readlane_b32 s29, v254, 49
	v_readlane_b32 s31, v254, 51
	v_cndmask_b32_e64 v18, 24, 25, vcc
	v_cmp_lt_u32_e32 vcc, 58, v16
	s_add_u32 s30, s28, s6
	v_mov_b32_e32 v253, 0
	v_cndmask_b32_e64 v39, 0, 1, vcc
	v_cmp_lt_u32_e32 vcc, s41, v16
	v_add_u32_e32 v16, 0xffffffbe, v17
	s_mov_b32 s5, 0
	v_addc_co_u32_e32 v39, vcc, v18, v39, vcc
	v_cmp_lt_u32_e32 vcc, 51, v16
	v_and_b32_e32 v246, 63, v244
	v_cmp_gt_u32_e64 s[2:3], 8, v245
	v_cndmask_b32_e64 v18, 24, 25, vcc
	v_cmp_lt_u32_e32 vcc, 58, v16
	v_mov_b32_e32 v143, v142
	v_mov_b32_e32 v144, v142
	v_cndmask_b32_e64 v40, 0, 1, vcc
	v_cmp_lt_u32_e32 vcc, s41, v16
	v_add_u32_e32 v16, 0xffffffbd, v17
	v_mov_b32_e32 v145, v142
	v_addc_co_u32_e32 v40, vcc, v18, v40, vcc
	v_cmp_lt_u32_e32 vcc, 51, v16
	v_lshl_add_u64 v[166:167], v[10:11], 0, v[14:15]
	s_addc_u32 s31, s29, s7
	v_cndmask_b32_e64 v18, 24, 25, vcc
	v_cmp_lt_u32_e32 vcc, 58, v16
	v_mov_b32_e32 v236, 0xf149f2ca
	v_add_u32_e32 v249, v29, v20
	v_cndmask_b32_e64 v41, 0, 1, vcc
	v_cmp_lt_u32_e32 vcc, s41, v16
	v_add_u32_e32 v16, 0xffffffb0, v17
	v_add_u32_e32 v250, v30, v140
	v_addc_co_u32_e32 v41, vcc, v18, v41, vcc
	v_cmp_lt_u32_e32 vcc, 39, v16
	v_add_u32_e32 v251, v26, v56
	v_add_u32_e32 v252, v31, v21
	v_cndmask_b32_e64 v18, 22, 23, vcc
	v_cmp_lt_u32_e32 vcc, 45, v16
	v_mov_b32_e32 v30, 0
	v_mov_b32_e32 v31, v253
	v_cndmask_b32_e64 v42, 0, 1, vcc
	v_cmp_lt_u32_e32 vcc, 51, v16
	v_add_u32_e32 v16, 0xffffffaf, v17
	v_mov_b32_e32 v20, v253
	v_addc_co_u32_e32 v42, vcc, v18, v42, vcc
	v_cmp_lt_u32_e32 vcc, 39, v16
	v_mov_b32_e32 v21, v253
	v_mov_b32_e32 v14, 0
	v_cndmask_b32_e64 v18, 22, 23, vcc
	v_cmp_lt_u32_e32 vcc, 45, v16
	v_mov_b32_e32 v15, v253
	v_mov_b32_e32 v26, 0
	v_cndmask_b32_e64 v43, 0, 1, vcc
	v_cmp_lt_u32_e32 vcc, 51, v16
	v_add_u32_e32 v16, 0xffffffae, v17
	v_mov_b32_e32 v29, v253
	v_addc_co_u32_e32 v43, vcc, v18, v43, vcc
	v_cmp_lt_u32_e32 vcc, 34, v16
	v_readlane_b32 s17, v254, 29
	v_readlane_b32 s18, v254, 30
	v_cndmask_b32_e64 v18, 21, 22, vcc
	v_cmp_lt_u32_e32 vcc, 39, v16
	v_readlane_b32 s19, v254, 31
	v_readlane_b32 s25, v254, 45
	v_addc_co_u32_e32 v18, vcc, 0, v18, vcc
	v_cmp_lt_u32_e32 vcc, 45, v16
	v_readlane_b32 s26, v254, 46
	v_readlane_b32 s27, v254, 47
	v_cndmask_b32_e64 v44, 0, 1, vcc
	v_cmp_lt_u32_e32 vcc, 51, v16
	v_add_u32_e32 v16, 0xffffffad, v17
	s_nop 0
	v_addc_co_u32_e32 v44, vcc, v18, v44, vcc
	v_cmp_lt_u32_e32 vcc, 34, v16
	s_nop 1
	v_cndmask_b32_e64 v18, 21, 22, vcc
	v_cmp_lt_u32_e32 vcc, 39, v16
	s_nop 1
	v_addc_co_u32_e32 v18, vcc, 0, v18, vcc
	v_cmp_lt_u32_e32 vcc, 45, v16
	s_nop 1
	v_cndmask_b32_e64 v45, 0, 1, vcc
	v_cmp_lt_u32_e32 vcc, 51, v16
	v_add_u32_e32 v16, 0xffffffa0, v17
	s_nop 0
	v_addc_co_u32_e32 v45, vcc, v18, v45, vcc
	v_cmp_lt_u32_e32 vcc, 20, v16
	s_nop 1
	v_cndmask_b32_e64 v18, 17, 18, vcc
	v_cmp_lt_u32_e32 vcc, 23, v16
	s_nop 1
	v_cndmask_b32_e64 v46, 0, 1, vcc
	v_cmp_lt_u32_e32 vcc, 26, v16
	s_nop 1
	v_addc_co_u32_e32 v18, vcc, v18, v46, vcc
	v_cmp_lt_u32_e32 vcc, 30, v16
	s_nop 1
	v_cndmask_b32_e64 v46, 0, 1, vcc
	v_cmp_lt_u32_e32 vcc, 34, v16
	v_add_u32_e32 v16, 0xffffff9f, v17
	s_nop 0
	v_addc_co_u32_e32 v46, vcc, v18, v46, vcc
	v_cmp_lt_u32_e32 vcc, 20, v16
	s_nop 1
	v_cndmask_b32_e64 v18, 17, 18, vcc
	v_cmp_lt_u32_e32 vcc, 23, v16
	s_nop 1
	v_cndmask_b32_e64 v47, 0, 1, vcc
	v_cmp_lt_u32_e32 vcc, 26, v16
	s_nop 1
	v_addc_co_u32_e32 v18, vcc, v18, v47, vcc
	v_cmp_lt_u32_e32 vcc, 30, v16
	s_nop 1
	v_cndmask_b32_e64 v47, 0, 1, vcc
	v_cmp_lt_u32_e32 vcc, 34, v16
	v_add_u32_e32 v16, 0xffffff9e, v17
	s_nop 0
	v_addc_co_u32_e32 v47, vcc, v18, v47, vcc
	v_cmp_lt_u32_e32 vcc, 18, v16
	s_nop 1
	v_cndmask_b32_e64 v18, 16, 17, vcc
	v_cmp_lt_u32_e32 vcc, 20, v16
	s_nop 1
	v_addc_co_u32_e32 v18, vcc, 0, v18, vcc
	v_cmp_lt_u32_e32 vcc, 23, v16
	s_nop 1
	v_cndmask_b32_e64 v48, 0, 1, vcc
	v_cmp_lt_u32_e32 vcc, 26, v16
	s_nop 1
	v_addc_co_u32_e32 v18, vcc, v18, v48, vcc
	v_cmp_lt_u32_e32 vcc, 30, v16
	s_nop 1
	v_cndmask_b32_e64 v48, 0, 1, vcc
	v_cmp_lt_u32_e32 vcc, 34, v16
	s_nop 1
	v_addc_co_u32_e32 v16, vcc, v18, v48, vcc
	v_add_u32_e32 v18, 0xffffff9d, v17
	v_cmp_lt_u32_e32 vcc, 18, v18
	v_lshlrev_b32_e32 v16, 4, v16
	s_nop 0
	v_cndmask_b32_e64 v48, 16, 17, vcc
	v_cmp_lt_u32_e32 vcc, 20, v18
	s_nop 1
	v_addc_co_u32_e32 v48, vcc, 0, v48, vcc
	v_cmp_lt_u32_e32 vcc, 23, v18
	s_nop 1
	v_cndmask_b32_e64 v49, 0, 1, vcc
	v_cmp_lt_u32_e32 vcc, 26, v18
	s_nop 1
	v_addc_co_u32_e32 v48, vcc, v48, v49, vcc
	v_cmp_lt_u32_e32 vcc, 30, v18
	s_nop 1
	v_cndmask_b32_e64 v49, 0, 1, vcc
	v_cmp_lt_u32_e32 vcc, 34, v18
	s_nop 1
	v_addc_co_u32_e32 v18, vcc, v48, v49, vcc
	v_add_u32_e32 v48, 0xffffff90, v17
	v_cmp_lt_u32_e32 vcc, 18, v48
	v_lshlrev_b32_e32 v18, 4, v18
	v_mov_b32_e32 v17, v141
	v_cndmask_b32_e64 v49, 16, 17, vcc
	v_cmp_lt_u32_e32 vcc, 20, v48
	v_lshl_add_u64 v[192:193], v[16:17], 2, v[146:147]
	v_mov_b32_e32 v16, v253
	v_addc_co_u32_e32 v49, vcc, 0, v49, vcc
	v_cmp_lt_u32_e32 vcc, 18, v50
	v_mov_b32_e32 v17, v253
	s_nop 0
	v_cndmask_b32_e64 v51, 16, 17, vcc
	v_cmp_lt_u32_e32 vcc, 20, v50
	s_nop 1
	v_addc_co_u32_e32 v51, vcc, 0, v51, vcc
	v_cmp_lt_u32_e32 vcc, 18, v52
	s_nop 1
	v_cndmask_b32_e64 v53, 16, 17, vcc
	v_cmp_lt_u32_e32 vcc, 20, v52
	s_nop 1
	v_addc_co_u32_e32 v53, vcc, 0, v53, vcc
	v_cmp_lt_u32_e32 vcc, 18, v54
	s_nop 1
	v_cndmask_b32_e64 v55, 16, 17, vcc
	v_cmp_gt_u32_e32 vcc, s35, v19
	v_mov_b32_e32 v19, v141
	v_lshl_add_u64 v[194:195], v[18:19], 2, v[10:11]
	v_cndmask_b32_e32 v12, v240, v241, vcc
	v_cmp_gt_u32_e32 vcc, s35, v22
	v_lshl_add_u64 v[148:149], v[146:147], 0, v[12:13]
	v_mov_b32_e32 v18, 0
	v_cndmask_b32_e32 v12, v240, v241, vcc
	v_cmp_gt_u32_e32 vcc, s42, v23
	v_lshl_add_u64 v[150:151], v[10:11], 0, v[12:13]
	v_mov_b32_e32 v19, v253
	v_cndmask_b32_e32 v12, v242, v27, vcc
	v_lshlrev_b32_e32 v12, 2, v12
	v_cmp_gt_u32_e32 vcc, s42, v24
	v_lshl_add_u64 v[152:153], v[146:147], 0, v[12:13]
	v_mov_b32_e32 v22, 0
	v_cndmask_b32_e32 v12, v242, v28, vcc
	v_lshlrev_b32_e32 v12, 2, v12
	v_lshl_add_u64 v[154:155], v[10:11], 0, v[12:13]
	v_lshlrev_b32_e32 v12, 6, v25
	v_lshl_add_u64 v[156:157], v[146:147], 0, v[12:13]
	v_lshlrev_b32_e32 v12, 6, v32
	v_lshl_add_u64 v[158:159], v[10:11], 0, v[12:13]
	v_lshlrev_b32_e32 v12, 6, v33
	v_lshl_add_u64 v[160:161], v[146:147], 0, v[12:13]
	v_lshlrev_b32_e32 v12, 6, v34
	v_lshl_add_u64 v[162:163], v[10:11], 0, v[12:13]
	v_lshlrev_b32_e32 v12, 6, v35
	v_lshl_add_u64 v[164:165], v[146:147], 0, v[12:13]
	v_lshlrev_b32_e32 v12, 6, v36
	v_lshl_add_u64 v[168:169], v[146:147], 0, v[12:13]
	v_lshlrev_b32_e32 v12, 6, v37
	v_lshl_add_u64 v[170:171], v[10:11], 0, v[12:13]
	v_lshlrev_b32_e32 v12, 6, v38
	v_lshl_add_u64 v[172:173], v[146:147], 0, v[12:13]
	v_lshlrev_b32_e32 v12, 6, v39
	v_lshl_add_u64 v[174:175], v[10:11], 0, v[12:13]
	v_lshlrev_b32_e32 v12, 6, v40
	v_lshl_add_u64 v[176:177], v[146:147], 0, v[12:13]
	v_lshlrev_b32_e32 v12, 6, v41
	v_lshl_add_u64 v[178:179], v[10:11], 0, v[12:13]
	v_lshlrev_b32_e32 v12, 6, v42
	v_lshl_add_u64 v[180:181], v[146:147], 0, v[12:13]
	v_lshlrev_b32_e32 v12, 6, v43
	v_lshl_add_u64 v[182:183], v[10:11], 0, v[12:13]
	v_lshlrev_b32_e32 v12, 6, v44
	v_lshl_add_u64 v[184:185], v[146:147], 0, v[12:13]
	v_lshlrev_b32_e32 v12, 6, v45
	v_lshl_add_u64 v[186:187], v[10:11], 0, v[12:13]
	v_lshlrev_b32_e32 v12, 6, v46
	v_lshl_add_u64 v[188:189], v[146:147], 0, v[12:13]
	v_lshlrev_b32_e32 v12, 6, v47
	v_cmp_gt_u32_e32 vcc, 16, v48
	v_lshl_add_u64 v[190:191], v[10:11], 0, v[12:13]
	v_mov_b32_e32 v38, 0
	v_cndmask_b32_e32 v12, v49, v48, vcc
	v_lshlrev_b32_e32 v12, 4, v12
	v_cmp_gt_u32_e32 vcc, 16, v50
	v_lshl_add_u64 v[196:197], v[12:13], 2, v[146:147]
	v_mov_b32_e32 v39, v253
	v_cndmask_b32_e32 v12, v51, v50, vcc
	v_lshlrev_b32_e32 v12, 4, v12
	v_cmp_gt_u32_e32 vcc, 16, v52
	v_lshl_add_u64 v[198:199], v[12:13], 2, v[10:11]
	v_mov_b32_e32 v40, v253
	v_cndmask_b32_e32 v12, v53, v52, vcc
	v_lshlrev_b32_e32 v12, 4, v12
	v_cmp_gt_u32_e32 vcc, 16, v54
	v_lshl_add_u64 v[200:201], v[12:13], 2, v[146:147]
	v_mov_b32_e32 v41, v253
	v_cndmask_b32_e32 v12, v55, v54, vcc
	v_lshlrev_b32_e32 v12, 4, v12
	v_lshl_add_u64 v[202:203], v[12:13], 2, v[10:11]
	v_mov_b32_e32 v34, 0
	v_mov_b32_e32 v35, v253
	v_mov_b32_e32 v36, v253
	v_mov_b32_e32 v37, v253
	v_mov_b32_e32 v32, v253
	v_mov_b32_e32 v33, v253
	v_mov_b32_e32 v10, 0
	v_mov_b32_e32 v11, v253
	v_mov_b32_e32 v12, v253
	v_mov_b32_e32 v13, v253
	v_mov_b32_e32 v23, v253
	v_mov_b32_e32 v24, v253
	v_mov_b32_e32 v25, v253
	v_mov_b32_e32 v27, v253
	v_mov_b32_e32 v28, v253
	s_load_dword s98, s[30:31], 0x0
.LBB0_721:
	s_movk_i32 s16, 0x800
	s_waitcnt lgkmcnt(0)
	s_mov_b32 s6, s98
	s_cmp_lt_u32 s5, 7
	s_cbranch_scc0 .Ldc_nopf
	s_load_dword s98, s[30:31], 0x4
.Ldc_nopf:
	s_ashr_i32 s7, s6, 31
	s_lshl_b64 s[6:7], s[6:7], 19
	s_add_u32 s12, s80, s6
	s_addc_u32 s13, s81, s7
	s_and_b32 s13, s13, 0xffff
	buffer_load_dwordx4 v[42:45], v247, s[12:15], 0 offen
	buffer_load_dwordx4 v[46:49], v247, s[12:15], s43 offen
	buffer_load_dwordx4 v[50:53], v247, s[12:15], s46 offen
	buffer_load_dwordx4 v[54:57], v247, s[12:15], s47 offen
	buffer_load_dwordx4 v[58:61], v247, s[12:15], s16 offen
	s_movk_i32 s16, 0x4800
	buffer_load_dwordx4 v[62:65], v247, s[12:15], s16 offen
	s_mov_b32 s16, 0x8800
	buffer_load_dwordx4 v[66:69], v247, s[12:15], s16 offen
	s_mov_b32 s16, 0xc800
	buffer_load_dwordx4 v[70:73], v247, s[12:15], s16 offen
	s_mov_b32 s16, 0x10800
	s_waitcnt vmcnt(7)
	v_cvt_pk_bf16_f32 v42, v42, v43
	v_cvt_pk_bf16_f32 v43, v44, v45
	ds_write_b64 v249, v[42:43]
	s_waitcnt vmcnt(6)
	v_cvt_pk_bf16_f32 v42, v46, v47
	v_cvt_pk_bf16_f32 v43, v48, v49
	ds_write_b64 v249, v[42:43] offset:576
	s_waitcnt vmcnt(5)
	v_cvt_pk_bf16_f32 v42, v50, v51
	v_cvt_pk_bf16_f32 v43, v52, v53
	ds_write_b64 v249, v[42:43] offset:1152
	s_waitcnt vmcnt(4)
	v_cvt_pk_bf16_f32 v42, v54, v55
	v_cvt_pk_bf16_f32 v43, v56, v57
	ds_write_b64 v249, v[42:43] offset:1728
	s_waitcnt vmcnt(3)
	v_cvt_pk_bf16_f32 v42, v58, v59
	v_cvt_pk_bf16_f32 v43, v60, v61
	ds_write_b64 v249, v[42:43] offset:2304
	s_waitcnt vmcnt(2)
	v_cvt_pk_bf16_f32 v42, v62, v63
	v_cvt_pk_bf16_f32 v43, v64, v65
	ds_write_b64 v249, v[42:43] offset:2880
	s_waitcnt vmcnt(1)
	v_cvt_pk_bf16_f32 v42, v66, v67
	v_cvt_pk_bf16_f32 v43, v68, v69
	ds_write_b64 v249, v[42:43] offset:3456
	s_waitcnt vmcnt(0)
	v_cvt_pk_bf16_f32 v74, v70, v71
	v_cvt_pk_bf16_f32 v75, v72, v73
	buffer_load_dwordx4 v[42:45], v247, s[12:15], s48 offen
	buffer_load_dwordx4 v[46:49], v247, s[12:15], s49 offen
	buffer_load_dwordx4 v[50:53], v247, s[12:15], s50 offen
	buffer_load_dwordx4 v[54:57], v247, s[12:15], s51 offen
	buffer_load_dwordx4 v[58:61], v247, s[12:15], s16 offen
	s_mov_b32 s16, 0x14800
	buffer_load_dwordx4 v[62:65], v247, s[12:15], s16 offen
	s_mov_b32 s16, 0x18800
	buffer_load_dwordx4 v[66:69], v247, s[12:15], s16 offen
	s_mov_b32 s16, 0x1c800
	buffer_load_dwordx4 v[70:73], v247, s[12:15], s16 offen
	ds_write_b64 v249, v[74:75] offset:4032
	s_waitcnt lgkmcnt(0)
	ds_read_b128 v[74:77], v250
	ds_read_b128 v[78:81], v250 offset:64
	s_waitcnt lgkmcnt(1)
	v_mfma_f32_16x16x32_bf16 v[74:77], v[74:77], v[2:5], 0
	ds_read_b128 v[82:85], v250 offset:2304
	s_add_u32 s16, s82, s6
	s_addc_u32 s6, s83, s7
	s_waitcnt lgkmcnt(1)
	v_mfma_f32_16x16x32_bf16 v[74:77], v[78:81], v[6:9], v[74:77]
	ds_read_b128 v[78:81], v250 offset:2368
	s_waitcnt lgkmcnt(1)
	v_mfma_f32_16x16x32_bf16 v[82:85], v[82:85], v[2:5], 0
	s_waitcnt lgkmcnt(0)
	v_mfma_f32_16x16x32_bf16 v[78:81], v[78:81], v[6:9], v[82:85]
	s_nop 7
	v_cndmask_b32_e64 v205, v81, v77, s[2:3]
	v_cndmask_b32_e64 v204, v80, v76, s[2:3]
	v_cndmask_b32_e64 v207, v79, v75, s[2:3]
	v_cndmask_b32_e64 v206, v78, v74, s[2:3]
	s_waitcnt vmcnt(7)
	v_cvt_pk_bf16_f32 v42, v42, v43
	v_cvt_pk_bf16_f32 v43, v44, v45
	ds_write_b64 v249, v[42:43] offset:4608
	s_waitcnt vmcnt(6)
	v_cvt_pk_bf16_f32 v42, v46, v47
	v_cvt_pk_bf16_f32 v43, v48, v49
	ds_write_b64 v249, v[42:43] offset:5184
	s_waitcnt vmcnt(5)
	v_cvt_pk_bf16_f32 v42, v50, v51
	v_cvt_pk_bf16_f32 v43, v52, v53
	ds_write_b64 v249, v[42:43] offset:5760
	s_waitcnt vmcnt(4)
	v_cvt_pk_bf16_f32 v42, v54, v55
	v_cvt_pk_bf16_f32 v43, v56, v57
	ds_write_b64 v249, v[42:43] offset:6336
	s_waitcnt vmcnt(3)
	v_cvt_pk_bf16_f32 v42, v58, v59
	v_cvt_pk_bf16_f32 v43, v60, v61
	ds_write_b64 v249, v[42:43] offset:6912
	s_waitcnt vmcnt(2)
	v_cvt_pk_bf16_f32 v42, v62, v63
	v_cvt_pk_bf16_f32 v43, v64, v65
	ds_write_b64 v249, v[42:43] offset:7488
	s_waitcnt vmcnt(1)
	v_cvt_pk_bf16_f32 v42, v66, v67
	v_cvt_pk_bf16_f32 v43, v68, v69
	s_mov_b32 s7, 0x20800
	ds_write_b64 v249, v[42:43] offset:8064
	s_waitcnt vmcnt(0)
	v_cvt_pk_bf16_f32 v74, v70, v71
	v_cvt_pk_bf16_f32 v75, v72, v73
	buffer_load_dwordx4 v[42:45], v247, s[12:15], s15 offen
	buffer_load_dwordx4 v[46:49], v247, s[12:15], s52 offen
	buffer_load_dwordx4 v[50:53], v247, s[12:15], s53 offen
	buffer_load_dwordx4 v[54:57], v247, s[12:15], s54 offen
	buffer_load_dwordx4 v[58:61], v247, s[12:15], s7 offen
	s_mov_b32 s7, 0x24800
	buffer_load_dwordx4 v[62:65], v247, s[12:15], s7 offen
	s_mov_b32 s7, 0x28800
	buffer_load_dwordx4 v[66:69], v247, s[12:15], s7 offen
	s_mov_b32 s7, 0x2c800
	buffer_load_dwordx4 v[70:73], v247, s[12:15], s7 offen
	ds_write_b64 v249, v[74:75] offset:8640
	s_waitcnt lgkmcnt(0)
	ds_read_b128 v[74:77], v250 offset:4608
	ds_read_b128 v[78:81], v250 offset:4672
	s_waitcnt lgkmcnt(1)
	v_mfma_f32_16x16x32_bf16 v[74:77], v[74:77], v[2:5], 0
	ds_read_b128 v[82:85], v250 offset:6912
	s_waitcnt lgkmcnt(1)
	v_mfma_f32_16x16x32_bf16 v[74:77], v[78:81], v[6:9], v[74:77]
	ds_read_b128 v[78:81], v250 offset:6976
	s_waitcnt lgkmcnt(1)
	v_mfma_f32_16x16x32_bf16 v[82:85], v[82:85], v[2:5], 0
	s_waitcnt lgkmcnt(0)
	v_mfma_f32_16x16x32_bf16 v[78:81], v[78:81], v[6:9], v[82:85]
	s_nop 7
	v_cndmask_b32_e64 v209, v81, v77, s[2:3]
	v_cndmask_b32_e64 v208, v80, v76, s[2:3]
	v_cndmask_b32_e64 v211, v79, v75, s[2:3]
	v_cndmask_b32_e64 v210, v78, v74, s[2:3]
	s_waitcnt vmcnt(7)
	v_cvt_pk_bf16_f32 v42, v42, v43
	v_cvt_pk_bf16_f32 v43, v44, v45
	ds_write_b64 v249, v[42:43]
	s_waitcnt vmcnt(6)
	v_cvt_pk_bf16_f32 v42, v46, v47
	v_cvt_pk_bf16_f32 v43, v48, v49
	ds_write_b64 v249, v[42:43] offset:576
	s_waitcnt vmcnt(5)
	v_cvt_pk_bf16_f32 v42, v50, v51
	v_cvt_pk_bf16_f32 v43, v52, v53
	ds_write_b64 v249, v[42:43] offset:1152
	s_waitcnt vmcnt(4)
	v_cvt_pk_bf16_f32 v42, v54, v55
	v_cvt_pk_bf16_f32 v43, v56, v57
	ds_write_b64 v249, v[42:43] offset:1728
	s_waitcnt vmcnt(3)
	v_cvt_pk_bf16_f32 v42, v58, v59
	v_cvt_pk_bf16_f32 v43, v60, v61
	ds_write_b64 v249, v[42:43] offset:2304
	s_waitcnt vmcnt(2)
	v_cvt_pk_bf16_f32 v42, v62, v63
	v_cvt_pk_bf16_f32 v43, v64, v65
	ds_write_b64 v249, v[42:43] offset:2880
	s_waitcnt vmcnt(1)
	v_cvt_pk_bf16_f32 v42, v66, v67
	v_cvt_pk_bf16_f32 v43, v68, v69
	s_mov_b32 s7, 0x30800
	ds_write_b64 v249, v[42:43] offset:3456
	s_waitcnt vmcnt(0)
	v_cvt_pk_bf16_f32 v74, v70, v71
	v_cvt_pk_bf16_f32 v75, v72, v73
	buffer_load_dwordx4 v[42:45], v247, s[12:15], s55 offen
	buffer_load_dwordx4 v[46:49], v247, s[12:15], s56 offen
	buffer_load_dwordx4 v[50:53], v247, s[12:15], s57 offen
	buffer_load_dwordx4 v[54:57], v247, s[12:15], s62 offen
	buffer_load_dwordx4 v[58:61], v247, s[12:15], s7 offen
	s_mov_b32 s7, 0x34800
	buffer_load_dwordx4 v[62:65], v247, s[12:15], s7 offen
	s_mov_b32 s7, 0x38800
	buffer_load_dwordx4 v[66:69], v247, s[12:15], s7 offen
	s_mov_b32 s7, 0x3c800
	buffer_load_dwordx4 v[70:73], v247, s[12:15], s7 offen
	ds_write_b64 v249, v[74:75] offset:4032
	s_waitcnt lgkmcnt(0)
	ds_read_b128 v[74:77], v250
	ds_read_b128 v[78:81], v250 offset:64
	s_waitcnt lgkmcnt(1)
	v_mfma_f32_16x16x32_bf16 v[74:77], v[74:77], v[2:5], 0
	ds_read_b128 v[82:85], v250 offset:2304
	s_waitcnt lgkmcnt(1)
	v_mfma_f32_16x16x32_bf16 v[74:77], v[78:81], v[6:9], v[74:77]
	ds_read_b128 v[78:81], v250 offset:2368
	s_waitcnt lgkmcnt(1)
	v_mfma_f32_16x16x32_bf16 v[82:85], v[82:85], v[2:5], 0
	s_waitcnt lgkmcnt(0)
	v_mfma_f32_16x16x32_bf16 v[78:81], v[78:81], v[6:9], v[82:85]
	s_nop 7
	v_cndmask_b32_e64 v213, v81, v77, s[2:3]
	v_cndmask_b32_e64 v212, v80, v76, s[2:3]
	v_cndmask_b32_e64 v215, v79, v75, s[2:3]
	v_cndmask_b32_e64 v214, v78, v74, s[2:3]
	s_waitcnt vmcnt(7)
	v_cvt_pk_bf16_f32 v42, v42, v43
	v_cvt_pk_bf16_f32 v43, v44, v45
	ds_write_b64 v249, v[42:43] offset:4608
	s_waitcnt vmcnt(6)
	v_cvt_pk_bf16_f32 v42, v46, v47
	v_cvt_pk_bf16_f32 v43, v48, v49
	ds_write_b64 v249, v[42:43] offset:5184
	s_waitcnt vmcnt(5)
	v_cvt_pk_bf16_f32 v42, v50, v51
	v_cvt_pk_bf16_f32 v43, v52, v53
	ds_write_b64 v249, v[42:43] offset:5760
	s_waitcnt vmcnt(4)
	v_cvt_pk_bf16_f32 v42, v54, v55
	v_cvt_pk_bf16_f32 v43, v56, v57
	ds_write_b64 v249, v[42:43] offset:6336
	s_waitcnt vmcnt(3)
	v_cvt_pk_bf16_f32 v42, v58, v59
	v_cvt_pk_bf16_f32 v43, v60, v61
	ds_write_b64 v249, v[42:43] offset:6912
	s_waitcnt vmcnt(2)
	v_cvt_pk_bf16_f32 v42, v62, v63
	v_cvt_pk_bf16_f32 v43, v64, v65
	ds_write_b64 v249, v[42:43] offset:7488
	s_waitcnt vmcnt(1)
	v_cvt_pk_bf16_f32 v42, v66, v67
	v_cvt_pk_bf16_f32 v43, v68, v69
	s_mov_b32 s7, 0x40800
	ds_write_b64 v249, v[42:43] offset:8064
	s_waitcnt vmcnt(0)
	v_cvt_pk_bf16_f32 v74, v70, v71
	v_cvt_pk_bf16_f32 v75, v72, v73
	buffer_load_dwordx4 v[42:45], v247, s[12:15], s63 offen
	buffer_load_dwordx4 v[46:49], v247, s[12:15], s64 offen
	buffer_load_dwordx4 v[50:53], v247, s[12:15], s65 offen
	buffer_load_dwordx4 v[54:57], v247, s[12:15], s66 offen
	buffer_load_dwordx4 v[58:61], v247, s[12:15], s7 offen
	s_mov_b32 s7, 0x44800
	buffer_load_dwordx4 v[62:65], v247, s[12:15], s7 offen
	s_mov_b32 s7, 0x48800
	buffer_load_dwordx4 v[66:69], v247, s[12:15], s7 offen
	s_mov_b32 s7, 0x4c800
	buffer_load_dwordx4 v[70:73], v247, s[12:15], s7 offen
	ds_write_b64 v249, v[74:75] offset:8640
	s_waitcnt lgkmcnt(0)
	ds_read_b128 v[74:77], v250 offset:4608
	ds_read_b128 v[78:81], v250 offset:4672
	s_waitcnt lgkmcnt(1)
	v_mfma_f32_16x16x32_bf16 v[74:77], v[74:77], v[2:5], 0
	ds_read_b128 v[82:85], v250 offset:6912
	s_waitcnt lgkmcnt(1)
	v_mfma_f32_16x16x32_bf16 v[74:77], v[78:81], v[6:9], v[74:77]
	ds_read_b128 v[78:81], v250 offset:6976
	s_waitcnt lgkmcnt(1)
	v_mfma_f32_16x16x32_bf16 v[82:85], v[82:85], v[2:5], 0
	s_waitcnt lgkmcnt(0)
	v_mfma_f32_16x16x32_bf16 v[78:81], v[78:81], v[6:9], v[82:85]
	s_nop 7
	v_cndmask_b32_e64 v217, v81, v77, s[2:3]
	v_cndmask_b32_e64 v216, v80, v76, s[2:3]
	v_cndmask_b32_e64 v219, v79, v75, s[2:3]
	v_cndmask_b32_e64 v218, v78, v74, s[2:3]
	s_waitcnt vmcnt(7)
	v_cvt_pk_bf16_f32 v42, v42, v43
	v_cvt_pk_bf16_f32 v43, v44, v45
	ds_write_b64 v249, v[42:43]
	s_waitcnt vmcnt(6)
	v_cvt_pk_bf16_f32 v42, v46, v47
	v_cvt_pk_bf16_f32 v43, v48, v49
	ds_write_b64 v249, v[42:43] offset:576
	s_waitcnt vmcnt(5)
	v_cvt_pk_bf16_f32 v42, v50, v51
	v_cvt_pk_bf16_f32 v43, v52, v53
	ds_write_b64 v249, v[42:43] offset:1152
	s_waitcnt vmcnt(4)
	v_cvt_pk_bf16_f32 v42, v54, v55
	v_cvt_pk_bf16_f32 v43, v56, v57
	ds_write_b64 v249, v[42:43] offset:1728
	s_waitcnt vmcnt(3)
	v_cvt_pk_bf16_f32 v42, v58, v59
	v_cvt_pk_bf16_f32 v43, v60, v61
	ds_write_b64 v249, v[42:43] offset:2304
	s_waitcnt vmcnt(2)
	v_cvt_pk_bf16_f32 v42, v62, v63
	v_cvt_pk_bf16_f32 v43, v64, v65
	ds_write_b64 v249, v[42:43] offset:2880
	s_waitcnt vmcnt(1)
	v_cvt_pk_bf16_f32 v42, v66, v67
	v_cvt_pk_bf16_f32 v43, v68, v69
	s_mov_b32 s7, 0x50800
	ds_write_b64 v249, v[42:43] offset:3456
	s_waitcnt vmcnt(0)
	v_cvt_pk_bf16_f32 v74, v70, v71
	v_cvt_pk_bf16_f32 v75, v72, v73
	buffer_load_dwordx4 v[42:45], v247, s[12:15], s67 offen
	buffer_load_dwordx4 v[46:49], v247, s[12:15], s68 offen
	buffer_load_dwordx4 v[50:53], v247, s[12:15], s69 offen
	buffer_load_dwordx4 v[54:57], v247, s[12:15], s84 offen
	buffer_load_dwordx4 v[58:61], v247, s[12:15], s7 offen
	s_mov_b32 s7, 0x54800
	buffer_load_dwordx4 v[62:65], v247, s[12:15], s7 offen
	s_mov_b32 s7, 0x58800
	buffer_load_dwordx4 v[66:69], v247, s[12:15], s7 offen
	s_mov_b32 s7, 0x5c800
	buffer_load_dwordx4 v[70:73], v247, s[12:15], s7 offen
	ds_write_b64 v249, v[74:75] offset:4032
	s_waitcnt lgkmcnt(0)
	ds_read_b128 v[74:77], v250
	ds_read_b128 v[78:81], v250 offset:64
	s_waitcnt lgkmcnt(1)
	v_mfma_f32_16x16x32_bf16 v[74:77], v[74:77], v[2:5], 0
	ds_read_b128 v[82:85], v250 offset:2304
	s_waitcnt lgkmcnt(1)
	v_mfma_f32_16x16x32_bf16 v[74:77], v[78:81], v[6:9], v[74:77]
	ds_read_b128 v[78:81], v250 offset:2368
	s_waitcnt lgkmcnt(1)
	v_mfma_f32_16x16x32_bf16 v[82:85], v[82:85], v[2:5], 0
	s_waitcnt lgkmcnt(0)
	v_mfma_f32_16x16x32_bf16 v[78:81], v[78:81], v[6:9], v[82:85]
	s_nop 7
	v_cndmask_b32_e64 v221, v81, v77, s[2:3]
	v_cndmask_b32_e64 v220, v80, v76, s[2:3]
	v_cndmask_b32_e64 v223, v79, v75, s[2:3]
	v_cndmask_b32_e64 v222, v78, v74, s[2:3]
	s_waitcnt vmcnt(7)
	v_cvt_pk_bf16_f32 v42, v42, v43
	v_cvt_pk_bf16_f32 v43, v44, v45
	ds_write_b64 v249, v[42:43] offset:4608
	s_waitcnt vmcnt(6)
	v_cvt_pk_bf16_f32 v42, v46, v47
	v_cvt_pk_bf16_f32 v43, v48, v49
	ds_write_b64 v249, v[42:43] offset:5184
	s_waitcnt vmcnt(5)
	v_cvt_pk_bf16_f32 v42, v50, v51
	v_cvt_pk_bf16_f32 v43, v52, v53
	ds_write_b64 v249, v[42:43] offset:5760
	s_waitcnt vmcnt(4)
	v_cvt_pk_bf16_f32 v42, v54, v55
	v_cvt_pk_bf16_f32 v43, v56, v57
	ds_write_b64 v249, v[42:43] offset:6336
	s_waitcnt vmcnt(3)
	v_cvt_pk_bf16_f32 v42, v58, v59
	v_cvt_pk_bf16_f32 v43, v60, v61
	ds_write_b64 v249, v[42:43] offset:6912
	s_waitcnt vmcnt(2)
	v_cvt_pk_bf16_f32 v42, v62, v63
	v_cvt_pk_bf16_f32 v43, v64, v65
	ds_write_b64 v249, v[42:43] offset:7488
	s_waitcnt vmcnt(1)
	v_cvt_pk_bf16_f32 v42, v66, v67
	v_cvt_pk_bf16_f32 v43, v68, v69
	s_mov_b32 s7, 0x60800
	ds_write_b64 v249, v[42:43] offset:8064
	s_waitcnt vmcnt(0)
	v_cvt_pk_bf16_f32 v74, v70, v71
	v_cvt_pk_bf16_f32 v75, v72, v73
	buffer_load_dwordx4 v[42:45], v247, s[12:15], s85 offen
	buffer_load_dwordx4 v[46:49], v247, s[12:15], s86 offen
	buffer_load_dwordx4 v[50:53], v247, s[12:15], s87 offen
	buffer_load_dwordx4 v[54:57], v247, s[12:15], s92 offen
	buffer_load_dwordx4 v[58:61], v247, s[12:15], s7 offen
	s_mov_b32 s7, 0x64800
	buffer_load_dwordx4 v[62:65], v247, s[12:15], s7 offen
	s_mov_b32 s7, 0x68800
	buffer_load_dwordx4 v[66:69], v247, s[12:15], s7 offen
	s_mov_b32 s7, 0x6c800
	buffer_load_dwordx4 v[70:73], v247, s[12:15], s7 offen
	ds_write_b64 v249, v[74:75] offset:8640
	s_waitcnt lgkmcnt(0)
	ds_read_b128 v[74:77], v250 offset:4608
	ds_read_b128 v[78:81], v250 offset:4672
	s_waitcnt lgkmcnt(1)
	v_mfma_f32_16x16x32_bf16 v[74:77], v[74:77], v[2:5], 0
	ds_read_b128 v[82:85], v250 offset:6912
	s_waitcnt lgkmcnt(1)
	v_mfma_f32_16x16x32_bf16 v[74:77], v[78:81], v[6:9], v[74:77]
	ds_read_b128 v[78:81], v250 offset:6976
	s_waitcnt lgkmcnt(1)
	v_mfma_f32_16x16x32_bf16 v[82:85], v[82:85], v[2:5], 0
	s_waitcnt lgkmcnt(0)
	v_mfma_f32_16x16x32_bf16 v[78:81], v[78:81], v[6:9], v[82:85]
	s_nop 7
	v_cndmask_b32_e64 v225, v81, v77, s[2:3]
	v_cndmask_b32_e64 v224, v80, v76, s[2:3]
	v_cndmask_b32_e64 v227, v79, v75, s[2:3]
	v_cndmask_b32_e64 v226, v78, v74, s[2:3]
	s_waitcnt vmcnt(7)
	v_cvt_pk_bf16_f32 v42, v42, v43
	v_cvt_pk_bf16_f32 v43, v44, v45
	ds_write_b64 v249, v[42:43]
	s_waitcnt vmcnt(6)
	v_cvt_pk_bf16_f32 v42, v46, v47
	v_cvt_pk_bf16_f32 v43, v48, v49
	ds_write_b64 v249, v[42:43] offset:576
	s_waitcnt vmcnt(5)
	v_cvt_pk_bf16_f32 v42, v50, v51
	v_cvt_pk_bf16_f32 v43, v52, v53
	ds_write_b64 v249, v[42:43] offset:1152
	s_waitcnt vmcnt(4)
	v_cvt_pk_bf16_f32 v42, v54, v55
	v_cvt_pk_bf16_f32 v43, v56, v57
	ds_write_b64 v249, v[42:43] offset:1728
	s_waitcnt vmcnt(3)
	v_cvt_pk_bf16_f32 v42, v58, v59
	v_cvt_pk_bf16_f32 v43, v60, v61
	ds_write_b64 v249, v[42:43] offset:2304
	s_waitcnt vmcnt(2)
	v_cvt_pk_bf16_f32 v42, v62, v63
	v_cvt_pk_bf16_f32 v43, v64, v65
	ds_write_b64 v249, v[42:43] offset:2880
	s_waitcnt vmcnt(1)
	v_cvt_pk_bf16_f32 v42, v66, v67
	v_cvt_pk_bf16_f32 v43, v68, v69
	s_mov_b32 s7, 0x70800
	ds_write_b64 v249, v[42:43] offset:3456
	s_waitcnt vmcnt(0)
	v_cvt_pk_bf16_f32 v74, v70, v71
	v_cvt_pk_bf16_f32 v75, v72, v73
	buffer_load_dwordx4 v[42:45], v247, s[12:15], s94 offen
	buffer_load_dwordx4 v[46:49], v247, s[12:15], s95 offen
	buffer_load_dwordx4 v[50:53], v247, s[12:15], s96 offen
	buffer_load_dwordx4 v[54:57], v247, s[12:15], s97 offen
	buffer_load_dwordx4 v[58:61], v247, s[12:15], s7 offen
	s_mov_b32 s7, 0x74800
	buffer_load_dwordx4 v[62:65], v247, s[12:15], s7 offen
	s_mov_b32 s7, 0x78800
	buffer_load_dwordx4 v[66:69], v247, s[12:15], s7 offen
	s_mov_b32 s7, 0x7c800
	buffer_load_dwordx4 v[70:73], v247, s[12:15], s7 offen
	ds_write_b64 v249, v[74:75] offset:4032
	s_waitcnt lgkmcnt(0)
	ds_read_b128 v[74:77], v250
	ds_read_b128 v[78:81], v250 offset:64
	s_waitcnt lgkmcnt(1)
	v_mfma_f32_16x16x32_bf16 v[74:77], v[74:77], v[2:5], 0
	ds_read_b128 v[82:85], v250 offset:2304
	s_waitcnt lgkmcnt(1)
	v_mfma_f32_16x16x32_bf16 v[74:77], v[78:81], v[6:9], v[74:77]
	ds_read_b128 v[78:81], v250 offset:2368
	s_waitcnt lgkmcnt(1)
	v_mfma_f32_16x16x32_bf16 v[82:85], v[82:85], v[2:5], 0
	s_waitcnt lgkmcnt(0)
	v_mfma_f32_16x16x32_bf16 v[78:81], v[78:81], v[6:9], v[82:85]
	s_nop 7
	v_cndmask_b32_e64 v233, v81, v77, s[2:3]
	v_cndmask_b32_e64 v232, v80, v76, s[2:3]
	v_cndmask_b32_e64 v235, v79, v75, s[2:3]
	v_cndmask_b32_e64 v234, v78, v74, s[2:3]
	s_waitcnt vmcnt(7)
	v_cvt_pk_bf16_f32 v42, v42, v43
	v_cvt_pk_bf16_f32 v43, v44, v45
	ds_write_b64 v249, v[42:43] offset:4608
	s_waitcnt vmcnt(6)
	v_cvt_pk_bf16_f32 v42, v46, v47
	v_cvt_pk_bf16_f32 v43, v48, v49
	ds_write_b64 v249, v[42:43] offset:5184
	s_waitcnt vmcnt(5)
	v_cvt_pk_bf16_f32 v42, v50, v51
	v_cvt_pk_bf16_f32 v43, v52, v53
	ds_write_b64 v249, v[42:43] offset:5760
	s_waitcnt vmcnt(4)
	v_cvt_pk_bf16_f32 v42, v54, v55
	v_cvt_pk_bf16_f32 v43, v56, v57
	ds_write_b64 v249, v[42:43] offset:6336
	s_waitcnt vmcnt(3)
	v_cvt_pk_bf16_f32 v42, v58, v59
	v_cvt_pk_bf16_f32 v43, v60, v61
	ds_write_b64 v249, v[42:43] offset:6912
	s_waitcnt vmcnt(2)
	v_cvt_pk_bf16_f32 v42, v62, v63
	v_cvt_pk_bf16_f32 v43, v64, v65
	ds_write_b64 v249, v[42:43] offset:7488
	s_waitcnt vmcnt(1)
	v_cvt_pk_bf16_f32 v42, v66, v67
	v_cvt_pk_bf16_f32 v43, v68, v69
	ds_write_b64 v249, v[42:43] offset:8064
	s_waitcnt vmcnt(0)
	v_cvt_pk_bf16_f32 v42, v70, v71
	v_cvt_pk_bf16_f32 v43, v72, v73
	ds_write_b64 v249, v[42:43] offset:8640
	s_waitcnt lgkmcnt(0)
	ds_read_b128 v[42:45], v250 offset:4608
	ds_read_b128 v[46:49], v250 offset:4672
	s_waitcnt lgkmcnt(1)
	v_mfma_f32_16x16x32_bf16 v[42:45], v[42:45], v[2:5], 0
	ds_read_b128 v[50:53], v250 offset:6912
	s_waitcnt lgkmcnt(1)
	v_mfma_f32_16x16x32_bf16 v[42:45], v[46:49], v[6:9], v[42:45]
	ds_read_b128 v[46:49], v250 offset:6976
	s_waitcnt lgkmcnt(1)
	v_mfma_f32_16x16x32_bf16 v[50:53], v[50:53], v[2:5], 0
	s_waitcnt lgkmcnt(0)
	v_mfma_f32_16x16x32_bf16 v[46:49], v[46:49], v[6:9], v[50:53]
	s_nop 7
	v_cndmask_b32_e64 v231, v49, v45, s[2:3]
	v_cndmask_b32_e64 v230, v48, v44, s[2:3]
	v_cndmask_b32_e64 v229, v47, v43, s[2:3]
	v_cndmask_b32_e64 v228, v46, v42, s[2:3]
	s_and_b32 s17, s6, 0xffff
	s_mov_b32 s18, s14
	s_mov_b32 s19, s15
	s_movk_i32 s6, 0x2000
	buffer_load_dwordx4 v[98:101], v248, s[16:19], 0 offen
	buffer_load_dwordx4 v[94:97], v248, s[16:19], s6 offen
	buffer_load_dwordx4 v[90:93], v248, s[16:19], s43 offen
	buffer_load_dwordx4 v[86:89], v248, s[16:19], s46 offen
	s_mov_b32 s6, 0xa000
	buffer_load_dwordx4 v[82:85], v248, s[16:19], s6 offen
	s_mov_b32 s6, 0xe000
	buffer_load_dwordx4 v[74:77], v248, s[16:19], s6 offen
	buffer_load_dwordx4 v[78:81], v248, s[16:19], s47 offen
	buffer_load_dwordx4 v[70:73], v248, s[16:19], s48 offen
	s_mov_b32 s6, 0x12000
	buffer_load_dwordx4 v[66:69], v248, s[16:19], s6 offen
	s_mov_b32 s6, 0x16000
	buffer_load_dwordx4 v[58:61], v248, s[16:19], s6 offen
	buffer_load_dwordx4 v[62:65], v248, s[16:19], s49 offen
	buffer_load_dwordx4 v[54:57], v248, s[16:19], s50 offen
	s_movk_i32 s6, 0x6000
	buffer_load_dwordx4 v[102:105], v248, s[16:19], s6 offen
	buffer_load_dwordx4 v[46:49], v248, s[16:19], s51 offen
	s_mov_b32 s6, 0x1a000
	buffer_load_dwordx4 v[50:53], v248, s[16:19], s6 offen
	s_mov_b32 s6, 0x1e000
	buffer_load_dwordx4 v[42:45], v248, s[16:19], s6 offen
	s_cmp_eq_u32 s39, s5
	s_mov_b64 s[6:7], -1
	s_cbranch_scc1 .LBB0_723
	v_pk_add_f32 v[124:125], v[144:145], v[204:205]
	v_pk_add_f32 v[122:123], v[142:143], v[206:207]
	v_pk_add_f32 v[120:121], v[144:145], v[208:209]
	v_pk_add_f32 v[118:119], v[142:143], v[210:211]
	v_pk_add_f32 v[116:117], v[144:145], v[212:213]
	v_pk_add_f32 v[114:115], v[142:143], v[214:215]
	v_pk_add_f32 v[112:113], v[144:145], v[216:217]
	v_pk_add_f32 v[110:111], v[142:143], v[218:219]
	v_pk_add_f32 v[108:109], v[144:145], v[220:221]
	v_pk_add_f32 v[106:107], v[142:143], v[222:223]
	v_pk_add_f32 v[128:129], v[144:145], v[224:225]
	v_pk_add_f32 v[126:127], v[142:143], v[226:227]
	v_pk_add_f32 v[132:133], v[144:145], v[232:233]
	v_pk_add_f32 v[130:131], v[142:143], v[234:235]
	v_pk_add_f32 v[136:137], v[144:145], v[230:231]
	v_pk_add_f32 v[134:135], v[142:143], v[228:229]
	s_mov_b64 s[6:7], 0

	.amdhsa_kernel _Z6mk_fwd4Args
		.amdhsa_group_segment_fixed_size 0
		.amdhsa_private_segment_fixed_size 0
		.amdhsa_kernarg_size 488
		.amdhsa_user_sgpr_count 2
		.amdhsa_user_sgpr_dispatch_ptr 0
		.amdhsa_user_sgpr_queue_ptr 0
		.amdhsa_user_sgpr_kernarg_segment_ptr 1
		.amdhsa_user_sgpr_dispatch_id 0
		.amdhsa_user_sgpr_kernarg_preload_length 0
		.amdhsa_user_sgpr_kernarg_preload_offset 0
		.amdhsa_user_sgpr_private_segment_size 0
		.amdhsa_uses_dynamic_stack 0
		.amdhsa_enable_private_segment 0
		.amdhsa_system_sgpr_workgroup_id_x 1
		.amdhsa_system_sgpr_workgroup_id_y 0
		.amdhsa_system_sgpr_workgroup_id_z 0
		.amdhsa_system_sgpr_workgroup_info 0
		.amdhsa_system_vgpr_workitem_id 0
		.amdhsa_next_free_vgpr 256
		.amdhsa_next_free_sgpr 102
		.amdhsa_accum_offset 256
		.amdhsa_reserve_vcc 1
		.amdhsa_float_round_mode_32 0
		.amdhsa_float_round_mode_16_64 0
		.amdhsa_float_denorm_mode_32 3
		.amdhsa_float_denorm_mode_16_64 3
		.amdhsa_dx10_clamp 1
		.amdhsa_ieee_mode 1
		.amdhsa_fp16_overflow 0
		.amdhsa_tg_split 0
		.amdhsa_exception_fp_ieee_invalid_op 0
		.amdhsa_exception_fp_denorm_src 0
		.amdhsa_exception_fp_ieee_div_zero 0
		.amdhsa_exception_fp_ieee_overflow 0
		.amdhsa_exception_fp_ieee_underflow 0
		.amdhsa_exception_fp_ieee_inexact 0
		.amdhsa_exception_int_div_zero 0
	.end_amdhsa_kernel

amdhsa.kernels:
  - .agpr_count:     0
    .args:
      - .offset:         0
        .size:           232
        .value_kind:     by_value
      - .offset:         232
        .size:           4
        .value_kind:     hidden_block_count_x
      - .offset:         236
        .size:           4
        .value_kind:     hidden_block_count_y
      - .offset:         240
        .size:           4
        .value_kind:     hidden_block_count_z
      - .offset:         244
        .size:           2
        .value_kind:     hidden_group_size_x
      - .offset:         246
        .size:           2
        .value_kind:     hidden_group_size_y
      - .offset:         248
        .size:           2
        .value_kind:     hidden_group_size_z
      - .offset:         250
        .size:           2
        .value_kind:     hidden_remainder_x
      - .offset:         252
        .size:           2
        .value_kind:     hidden_remainder_y
      - .offset:         254
        .size:           2
        .value_kind:     hidden_remainder_z
      - .offset:         272
        .size:           8
        .value_kind:     hidden_global_offset_x
      - .offset:         280
        .size:           8
        .value_kind:     hidden_global_offset_y
      - .offset:         288
        .size:           8
        .value_kind:     hidden_global_offset_z
      - .offset:         296
        .size:           2
        .value_kind:     hidden_grid_dims
      - .offset:         352
        .size:           4
        .value_kind:     hidden_dynamic_lds_size
    .group_segment_fixed_size: 0
    .kernarg_segment_align: 8
    .kernarg_segment_size: 488
    .language:       OpenCL C
    .language_version:
      - 2
      - 0
    .max_flat_workgroup_size: 512
    .name:           _Z6mk_fwd4Args
    .private_segment_fixed_size: 0
    .sgpr_count:     108
    .sgpr_spill_count: 76
    .symbol:         _Z6mk_fwd4Args.kd
    .uniform_work_group_size: 1
    .uses_dynamic_stack: false
    .vgpr_count:     256
    .vgpr_spill_count: 0
    .wavefront_size: 64
